# LDS-free cross-half row max also in A2 online softmax (v_permlane32_swap, one-temp form) on top of v23
# baseline (speedup 1.0000x reference)
; DI float shx(float v, int o, int lane) { return __int_as_float(__builtin_amdgcn_ds_bpermute((lane ^ o) << 2, __float_as_int(v))); }
;     ...
;             float mx = -1e30f;
; #pragma unroll
;             for (int kb2 = 0; kb2 < NKB; ++kb2)
; #pragma unroll
;                 for (int i = 0; i < 16; ++i) mx = __builtin_fmaxf(mx, sv[kb2][i]);
;             mx = __builtin_fmaxf(mx, shx(mx, 32, lane));
;             if (__ballot(mx > 8.0f)) {
;                 const float delta = __builtin_fmaxf(mx, 0.f);
;                 const float alpha = __builtin_amdgcn_exp2f(-delta);
;                 nm_run -= delta; l_run *= alpha;
; #pragma unroll
;                 for (int kb2 = 0; kb2 < NKB; ++kb2)
; #pragma unroll
;                     for (int i = 0; i < 16; ++i) sv[kb2][i] -= delta;
; #pragma unroll
;                 for (int db = 0; db < NDB; ++db)
; #pragma unroll
;                     for (int i = 0; i < 16; ++i) ot[db][i] *= alpha;
;             }
.LBB0_505:
	s_nop 9
	v_max3_f32 v65, v82, s61, v83
	v_max3_f32 v65, v65, v84, v85
	v_max3_f32 v65, v65, v86, v87
	v_max3_f32 v65, v65, v88, v89
	v_max3_f32 v65, v65, v90, v91
	v_max3_f32 v65, v65, v92, v93
	v_max3_f32 v65, v65, v94, v95
	v_max3_f32 v65, v65, v96, v97
	v_max3_f32 v65, v65, v66, v67
	v_max3_f32 v65, v65, v68, v69
	v_max3_f32 v65, v65, v70, v71
	v_max3_f32 v65, v65, v72, v73
	v_max3_f32 v65, v65, v74, v75
	v_max3_f32 v65, v65, v76, v77
	v_max3_f32 v65, v65, v78, v79
	v_max3_f32 v65, v65, v80, v81
	v_mov_b32_e32 v196, v65
	s_nop 1
	v_permlane32_swap_b32 v196, v65
	s_nop 1
	v_max_f32_e32 v65, v65, v196
	s_waitcnt lgkmcnt(0)
	v_cmp_lt_f32_e32 vcc, s33, v65
	s_cbranch_vccz .LBB0_500
	v_max_f32_e32 v65, v65, v65
	v_max_f32_e32 v196, 0, v65
	v_exp_f32_e64 v218, -v196
	v_sub_f32_e32 v64, v64, v196
	v_pk_add_f32 v[82:83], v[82:83], v[196:197] op_sel_hi:[1,0] neg_lo:[0,1] neg_hi:[0,1]
	v_pk_add_f32 v[84:85], v[84:85], v[196:197] op_sel_hi:[1,0] neg_lo:[0,1] neg_hi:[0,1]
	v_pk_add_f32 v[86:87], v[86:87], v[196:197] op_sel_hi:[1,0] neg_lo:[0,1] neg_hi:[0,1]
	v_pk_add_f32 v[88:89], v[88:89], v[196:197] op_sel_hi:[1,0] neg_lo:[0,1] neg_hi:[0,1]
	v_pk_add_f32 v[90:91], v[90:91], v[196:197] op_sel_hi:[1,0] neg_lo:[0,1] neg_hi:[0,1]
	v_pk_add_f32 v[92:93], v[92:93], v[196:197] op_sel_hi:[1,0] neg_lo:[0,1] neg_hi:[0,1]
	v_pk_add_f32 v[94:95], v[94:95], v[196:197] op_sel_hi:[1,0] neg_lo:[0,1] neg_hi:[0,1]
	v_pk_add_f32 v[96:97], v[96:97], v[196:197] op_sel_hi:[1,0] neg_lo:[0,1] neg_hi:[0,1]
	v_pk_add_f32 v[66:67], v[66:67], v[196:197] op_sel_hi:[1,0] neg_lo:[0,1] neg_hi:[0,1]
	v_pk_add_f32 v[68:69], v[68:69], v[196:197] op_sel_hi:[1,0] neg_lo:[0,1] neg_hi:[0,1]
	v_pk_add_f32 v[70:71], v[70:71], v[196:197] op_sel_hi:[1,0] neg_lo:[0,1] neg_hi:[0,1]
	v_pk_add_f32 v[72:73], v[72:73], v[196:197] op_sel_hi:[1,0] neg_lo:[0,1] neg_hi:[0,1]
	v_pk_add_f32 v[74:75], v[74:75], v[196:197] op_sel_hi:[1,0] neg_lo:[0,1] neg_hi:[0,1]
	v_pk_add_f32 v[76:77], v[76:77], v[196:197] op_sel_hi:[1,0] neg_lo:[0,1] neg_hi:[0,1]
	v_pk_add_f32 v[78:79], v[78:79], v[196:197] op_sel_hi:[1,0] neg_lo:[0,1] neg_hi:[0,1]
	v_pk_add_f32 v[80:81], v[80:81], v[196:197] op_sel_hi:[1,0] neg_lo:[0,1] neg_hi:[0,1]
	v_pk_mul_f32 v[14:15], v[14:15], v[218:219] op_sel_hi:[1,0]
	v_pk_mul_f32 v[12:13], v[12:13], v[218:219] op_sel_hi:[1,0]
	v_pk_mul_f32 v[10:11], v[10:11], v[218:219] op_sel_hi:[1,0]
	v_pk_mul_f32 v[8:9], v[8:9], v[218:219] op_sel_hi:[1,0]
	v_pk_mul_f32 v[6:7], v[6:7], v[218:219] op_sel_hi:[1,0]
	v_pk_mul_f32 v[4:5], v[4:5], v[218:219] op_sel_hi:[1,0]
	v_pk_mul_f32 v[2:3], v[2:3], v[218:219] op_sel_hi:[1,0]
	v_pk_mul_f32 v[0:1], v[0:1], v[218:219] op_sel_hi:[1,0]
	v_pk_mul_f32 v[62:63], v[62:63], v[218:219] op_sel_hi:[1,0]
	v_pk_mul_f32 v[60:61], v[60:61], v[218:219] op_sel_hi:[1,0]
	v_pk_mul_f32 v[58:59], v[58:59], v[218:219] op_sel_hi:[1,0]
	v_pk_mul_f32 v[56:57], v[56:57], v[218:219] op_sel_hi:[1,0]
	v_pk_mul_f32 v[54:55], v[54:55], v[218:219] op_sel_hi:[1,0]
	v_pk_mul_f32 v[52:53], v[52:53], v[218:219] op_sel_hi:[1,0]
	v_pk_mul_f32 v[50:51], v[50:51], v[218:219] op_sel_hi:[1,0]
	v_pk_mul_f32 v[48:49], v[48:49], v[218:219] op_sel_hi:[1,0]
	v_pk_mul_f32 v[46:47], v[46:47], v[218:219] op_sel_hi:[1,0]
	v_pk_mul_f32 v[44:45], v[44:45], v[218:219] op_sel_hi:[1,0]
	v_pk_mul_f32 v[42:43], v[42:43], v[218:219] op_sel_hi:[1,0]
	v_pk_mul_f32 v[40:41], v[40:41], v[218:219] op_sel_hi:[1,0]
	v_pk_mul_f32 v[38:39], v[38:39], v[218:219] op_sel_hi:[1,0]
	v_pk_mul_f32 v[36:37], v[36:37], v[218:219] op_sel_hi:[1,0]
	v_pk_mul_f32 v[34:35], v[34:35], v[218:219] op_sel_hi:[1,0]
	v_pk_mul_f32 v[32:33], v[32:33], v[218:219] op_sel_hi:[1,0]
	v_pk_mul_f32 v[30:31], v[30:31], v[218:219] op_sel_hi:[1,0]
	v_pk_mul_f32 v[28:29], v[28:29], v[218:219] op_sel_hi:[1,0]
	v_pk_mul_f32 v[26:27], v[26:27], v[218:219] op_sel_hi:[1,0]
	v_pk_mul_f32 v[24:25], v[24:25], v[218:219] op_sel_hi:[1,0]
	v_pk_mul_f32 v[22:23], v[22:23], v[218:219] op_sel_hi:[1,0]
	v_pk_mul_f32 v[20:21], v[20:21], v[218:219] op_sel_hi:[1,0]
	v_pk_mul_f32 v[18:19], v[18:19], v[218:219] op_sel_hi:[1,0]
	v_pk_mul_f32 v[16:17], v[16:17], v[218:219] op_sel_hi:[1,0]
	v_mul_f32_e32 v212, v212, v218
	s_branch .LBB0_500
